# GLA even half: wave-uniform execz branch around the two masked LDS writes removed
# speedup vs baseline: 1.0010x; 1.0010x over previous
.LBB0_233:
	ds_read_b64_tr_b16 v[134:135], v117 offset:576
	ds_read_b64_tr_b16 v[132:133], v117
	ds_read_b128 v[136:139], v125 offset:18432
	ds_read_b64_tr_b16 v[142:143], v117 offset:608
	ds_read_b64_tr_b16 v[140:141], v117 offset:32
	ds_read_b128 v[144:147], v125 offset:18496
	ds_read_b64_tr_b16 v[150:151], v117 offset:4608
	ds_read_b64_tr_b16 v[152:153], v117 offset:5184
	ds_read_b64_tr_b16 v[156:157], v117 offset:5216
	ds_read_b64_tr_b16 v[154:155], v117 offset:4640
	s_waitcnt lgkmcnt(7)
	v_mfma_f32_16x16x32_bf16 v[50:53], v[132:135], v[136:139], v[50:53]
	ds_read_b64_tr_b16 v[158:159], v101 offset:55296
	ds_read_b64_tr_b16 v[160:161], v101 offset:55872
	v_add_u32_e32 v131, v94, v97
	s_waitcnt lgkmcnt(7)
	v_mfma_f32_16x16x32_bf16 v[136:139], v[140:143], v[136:139], v[54:57]
	s_waitcnt lgkmcnt(4)
	v_mfma_f32_16x16x32_bf16 v[50:53], v[150:153], v[144:147], v[50:53]
	s_nop 0
	v_add_u32_e32 v56, s29, v71
	v_add_u32_e32 v54, 64, v129
	v_cndmask_b32_e64 v54, v54, v56, s[0:1]
	s_waitcnt lgkmcnt(2)
	v_mfma_f32_16x16x32_bf16 v[136:139], v[154:157], v[144:147], v[136:139]
	ds_read_b64_tr_b16 v[144:145], v101 offset:59904
	ds_read_b64_tr_b16 v[146:147], v101 offset:60480
	v_add_u32_e32 v54, s30, v54
	v_ashrrev_i32_e32 v55, 31, v54
	s_waitcnt lgkmcnt(2)
	v_mfma_f32_16x16x32_bf16 v[46:49], v[158:161], v[132:135], v[46:49]
	v_cvt_pk_bf16_f32 v172, v50, v51
	v_cvt_pk_bf16_f32 v173, v52, v53
	ds_read_b128 v[50:53], v118 offset:46080
	v_mfma_f32_16x16x32_bf16 v[42:45], v[158:161], v[140:143], v[42:45]
	v_lshlrev_b64 v[54:55], 10, v[54:55]
	v_lshl_add_u64 v[54:55], v[80:81], 0, v[54:55]
	s_nop 0
	s_waitcnt lgkmcnt(1)
	v_mfma_f32_16x16x32_bf16 v[46:49], v[144:147], v[150:153], v[46:49]
	v_cvt_pk_bf16_f32 v174, v136, v137
	v_cvt_pk_bf16_f32 v175, v138, v139
	s_nop 1
	v_permlane16_swap_b32_e32 v172, v174
	v_permlane16_swap_b32_e32 v173, v175
	global_store_dwordx4 v[54:55], v[172:175], off
	v_mfma_f32_16x16x32_bf16 v[42:45], v[144:147], v[154:157], v[42:45]
	s_waitcnt vmcnt(8)
	v_lshlrev_b32_e32 v136, 16, v22
	s_waitcnt lgkmcnt(0)
	s_nop 0
	v_pk_mul_f32 v[48:49], v[52:53], v[48:49]
	v_pk_mul_f32 v[46:47], v[50:51], v[46:47]
	v_and_b32_e32 v137, 0xffff0000, v22
	v_lshlrev_b32_e32 v22, 16, v23
	v_pk_mul_f32 v[44:45], v[52:53], v[44:45]
	v_pk_mul_f32 v[42:43], v[50:51], v[42:43]
	v_cvt_pk_bf16_f32 v50, v46, v47
	v_cvt_pk_bf16_f32 v51, v48, v49
	ds_write_b64 v131, v[50:51] offset:27648
	v_cvt_pk_bf16_f32 v50, v42, v43
	v_cvt_pk_bf16_f32 v51, v44, v45
	ds_write_b64 v119, v[50:51] offset:27648
	ds_read_b128 v[50:53], v120
	ds_read_b128 v[132:135], v120 offset:16
	v_and_b32_e32 v23, 0xffff0000, v23
	v_lshlrev_b32_e32 v138, 16, v24
	v_and_b32_e32 v139, 0xffff0000, v24
	s_waitcnt lgkmcnt(1)
	v_exp_f32_e64 v54, -v50
	v_exp_f32_e64 v55, -v51
	v_exp_f32_e32 v50, v50
	v_exp_f32_e32 v51, v51
	s_waitcnt lgkmcnt(0)
	v_exp_f32_e32 v24, v134
	v_pk_mul_f32 v[54:55], v[54:55], v[136:137]
	s_waitcnt vmcnt(6)
	v_lshlrev_b32_e32 v136, 16, v18
	v_and_b32_e32 v137, 0xffff0000, v18
	v_pk_mul_f32 v[136:137], v[50:51], v[136:137]
	s_nop 0
	v_cvt_pk_bf16_f32 v18, v136, v137
	v_cvt_pk_bf16_f32 v136, v54, v55
	v_exp_f32_e64 v54, -v52
	v_exp_f32_e64 v55, -v53
	v_exp_f32_e32 v52, v52
	v_exp_f32_e32 v53, v53
	v_pk_mul_f32 v[22:23], v[54:55], v[22:23]
	v_lshlrev_b32_e32 v54, 16, v19
	v_and_b32_e32 v55, 0xffff0000, v19
	v_pk_mul_f32 v[54:55], v[52:53], v[54:55]
	v_cvt_pk_bf16_f32 v137, v22, v23
	v_cvt_pk_bf16_f32 v19, v54, v55
	v_exp_f32_e64 v54, -v132
	v_exp_f32_e64 v55, -v133
	v_exp_f32_e32 v22, v132
	v_exp_f32_e32 v23, v133
	v_lshlrev_b32_e32 v132, 16, v20
	v_pk_mul_f32 v[54:55], v[54:55], v[138:139]
	v_and_b32_e32 v133, 0xffff0000, v20
	v_pk_mul_f32 v[132:133], v[22:23], v[132:133]
	v_cvt_pk_bf16_f32 v138, v54, v55
	v_exp_f32_e64 v54, -v134
	v_exp_f32_e64 v55, -v135
	v_cvt_pk_bf16_f32 v20, v132, v133
	v_lshlrev_b32_e32 v132, 16, v25
	v_and_b32_e32 v133, 0xffff0000, v25
	v_exp_f32_e32 v25, v135
	v_pk_mul_f32 v[54:55], v[54:55], v[132:133]
	v_lshlrev_b32_e32 v132, 16, v21
	v_and_b32_e32 v133, 0xffff0000, v21
	v_pk_mul_f32 v[132:133], v[24:25], v[132:133]
	v_cvt_pk_bf16_f32 v139, v54, v55
	v_cvt_pk_bf16_f32 v21, v132, v133
	ds_write_b128 v111, v[18:21]
	ds_write_b128 v111, v[136:139] offset:64512
	s_and_saveexec_b64 s[26:27], vcc
	ds_write_b128 v126, v[50:53] offset:46336
	ds_write_b128 v126, v[22:25] offset:46352
